# P1: keep wave-half stagger across unit boundaries (drop per-unit ALIGN and re-stagger barriers), bias LDS double-buffered
# baseline (speedup 1.0000x reference)
.LBB0_378:
	s_lshl_b32 s65, s3, 6
	s_and_b32 s1, s1, 3
	v_or_b32_e32 v6, s65, v3
	v_lshlrev_b32_e32 v6, 7, v6
	s_lshl_b32 s3, s1, 5
	v_or_b32_e32 v8, v6, v192
	v_or_b32_e32 v9, v6, v193
	v_or_b32_e32 v6, s3, v3
	v_lshlrev_b32_e32 v6, 7, v6
	s_mov_b64 s[48:49], 0x80
	v_or_b32_e32 v10, v6, v192
	v_or_b32_e32 v11, v6, v193
	v_lshl_add_u64 v[6:7], v[4:5], 0, s[48:49]
	s_add_i32 m0, s79, 0x18000
	s_mov_b64 s[50:51], 0x40080
	s_waitcnt vmcnt(2)
	s_barrier
	global_load_lds_dwordx4 v[6:7], off
	v_lshl_add_u64 v[6:7], v[4:5], 0, s[50:51]
	s_add_i32 m0, s79, 0x1a000
	s_mov_b64 s[52:53], 0x10080
	global_load_lds_dwordx4 v[6:7], off
	v_lshl_add_u64 v[6:7], v[4:5], 0, s[52:53]
	s_add_i32 m0, s79, 0x1c000
	s_mov_b64 s[54:55], 0x50080
	global_load_lds_dwordx4 v[6:7], off
	v_lshl_add_u64 v[4:5], v[4:5], 0, s[54:55]
	s_add_i32 m0, s79, 0x1e000
	v_writelane_b32 v254, s34, 25
	global_load_lds_dwordx4 v[4:5], off
	s_nop 0
	v_writelane_b32 v254, s35, 26
	v_writelane_b32 v254, s26, 27
	s_mov_b32 s98, s0
	s_mov_b32 s99, 0
	s_cmpk_lt_u32 s0, 0x100
	v_or_b32_e32 v4, s3, v191
	v_writelane_b32 v254, s27, 28
	s_cselect_b64 s[56:57], -1, 0
	s_lshl_b32 s85, s1, 6
	s_ashr_i32 s3, s33, 31
	s_ashr_i32 s73, s2, 31
	v_readlane_b32 s0, v254, 13
	v_readlane_b32 s1, v254, 14
	s_add_u32 s58, s0, 0x783800
	s_addc_u32 s59, s1, 0
	s_add_u32 s60, s0, 0x784800
	s_mov_b32 s13, 0x14800
	s_addc_u32 s61, s1, 0
	s_addk_i32 s13, 0x100
	s_mov_b32 s12, 0x10800
	v_add_u32_e32 v205, s13, v10
	v_add_u32_e32 v206, s13, v11
	s_mov_b32 s13, 0x18800
	s_addk_i32 s12, 0x100
	s_addk_i32 s13, 0x100
	s_mov_b32 s8, 0x18000
	s_mov_b32 s9, 0x1c000
	s_waitcnt vmcnt(4)
	s_mov_b32 s1, 0x10000
	v_add_u32_e32 v201, s12, v10
	v_add_u32_e32 v202, s12, v11
	s_mov_b32 s12, 0x14000
	v_add_u32_e32 v209, s13, v10
	v_add_u32_e32 v210, s13, v11
	s_mov_b32 s13, 0x1c800
	v_lshlrev_b32_e32 v160, 1, v191
	s_addk_i32 s1, 0x100
	s_addk_i32 s12, 0x100
	s_addk_i32 s13, 0x100
	s_movk_i32 s68, 0xfc40
	s_movk_i32 s92, 0xa040
	s_add_i32 s70, s8, 0x100
	s_add_i32 s71, s9, 0x100
	v_or_b32_e32 v198, 0xfffff900, v4
	v_cmp_gt_u32_e64 s[6:7], 8, v3
	v_lshl_add_u64 v[162:163], s[42:43], 0, v[160:161]
	v_lshl_add_u64 v[164:165], s[34:35], 0, v[160:161]
	v_lshl_add_u64 v[166:167], s[26:27], 0, v[160:161]
	v_add_u32_e32 v168, v194, v186
	v_mov_b32_e32 v169, v161
	s_mov_b32 s0, 0
	v_mov_b64_e32 v[170:171], 0x580
	v_mov_b64_e32 v[172:173], 0x57f
	v_add_u32_e32 v199, s1, v10
	v_add_u32_e32 v200, s1, v11
	v_add_u32_e32 v203, s12, v10
	v_add_u32_e32 v204, s12, v11
	v_add_u32_e32 v207, 0x100, v8
	v_add_u32_e32 v208, 0x100, v9
	v_add_u32_e32 v211, s13, v10
	v_add_u32_e32 v212, s13, v11
	s_movk_i32 s13, 0xc00
	s_mov_b32 s69, -1
	s_mov_b32 s72, 0x3e000000
	s_mov_b32 s93, -1
	v_add_u32_e32 v213, s70, v10
	v_add_u32_e32 v214, s70, v11
	v_add_u32_e32 v215, s71, v10
	v_add_u32_e32 v216, s71, v11
	s_barrier
	s_branch .LBB0_381

.LBB0_383:
	s_ashr_i32 s67, s66, 31
	s_lshl_b64 s[26:27], s[66:67], 19
	s_add_u32 s26, s40, s26
	s_addc_u32 s27, s41, s27
	s_and_b64 s[34:35], s[8:9], exec
	s_cselect_b32 s34, s27, s5
	s_cselect_b32 s35, s26, s4
	s_ashr_i32 s29, s28, 31
	s_lshl_b64 s[38:39], s[28:29], 19
	s_add_u32 s62, s10, s38
	s_addc_u32 s63, s11, s39
	s_and_b64 s[38:39], s[8:9], exec
	s_cselect_b32 s29, s63, s83
	s_cselect_b32 s38, s62, s82
	s_add_u32 s39, s82, 0x100
	s_addc_u32 s67, s83, 0
	s_mov_b32 s94, -2
	s_mov_b64 vcc, 0
	v_lshl_add_u64 v[132:133], s[4:5], 0, v[168:169]
	ds_read_b128 v[134:137], v199
	ds_read_b128 v[138:141], v200
	ds_read_b128 v[142:145], v201
	ds_read_b128 v[146:149], v202
	ds_read_b128 v[150:153], v203
	ds_read_b128 v[174:177], v204
	ds_read_b128 v[178:181], v205
	ds_read_b128 v[182:185], v206
	s_add_u32 s24, s4, vcc_lo
	s_addc_u32 s25, s5, vcc_hi
	s_add_u32 s24, s24, 0x100
	s_addc_u32 s25, s25, 0
	s_add_u32 s82, s39, vcc_lo
	s_addc_u32 s83, s67, vcc_hi
	s_cmpk_eq_i32 vcc_lo, 0x700
	s_cselect_b32 s87, s29, s83
	s_cselect_b32 s86, s38, s82
	s_cselect_b32 s83, s34, s25
	s_cselect_b32 s82, s35, s24
	v_lshl_add_u64 v[154:155], v[132:133], 0, vcc
	v_lshl_add_u64 v[250:251], v[154:155], 0, s[48:49]
	s_add_i32 m0, s79, 0x8000
	s_mov_b64 s[24:25], 0x20080
	ds_read_b128 v[218:221], v207
	ds_read_b128 v[222:225], v207 offset:2048
	ds_read_b128 v[226:229], v208
	ds_read_b128 v[230:233], v208 offset:2048
	ds_read_b128 v[234:237], v207 offset:4096
	ds_read_b128 v[238:241], v207 offset:6144
	ds_read_b128 v[242:245], v208 offset:4096
	ds_read_b128 v[246:249], v208 offset:6144
	global_load_lds_dwordx4 v[250:251], off
	v_lshl_add_u64 v[250:251], v[154:155], 0, s[24:25]
	s_add_i32 m0, s79, 0xa000
	s_mov_b64 s[24:25], 0x60080
	global_load_lds_dwordx4 v[250:251], off
	v_lshl_add_u64 v[250:251], v[154:155], 0, s[50:51]
	s_add_i32 m0, s79, 0xc000
	v_lshl_add_u64 v[154:155], v[154:155], 0, s[24:25]
	global_load_lds_dwordx4 v[250:251], off
	s_add_i32 m0, s79, 0xe000
	s_nop 0
	global_load_lds_dwordx4 v[154:155], off
	s_waitcnt vmcnt(16)
	s_waitcnt lgkmcnt(0)
	s_barrier
	s_xor_b32 s99, s99, 0x400
	s_cmp_lg_u32 s98, 0
	s_cbranch_scc1 .Lp1b_skip
	v_mbcnt_lo_u32_b32 v255, -1, 0
	v_mbcnt_hi_u32_b32 v255, -1, v255
	s_cmp_gt_i32 s96, 13
	s_cbranch_scc1 .Lp1b_gate
	s_lshl_b32 s100, s96, 10
	s_add_u32 s100, s90, s100
	s_addc_u32 s101, s91, 0
	v_lshlrev_b32_e32 v255, 4, v255
	s_branch .Lp1b_issue

.Lp1b_issue:
	s_add_i32 m0, s99, 0x21000
	s_nop 0
	global_load_lds_dwordx4 v255, s[100:101]

.LBB0_384:
	ds_read_b128 v[134:137], v199
	ds_read_b128 v[138:141], v200
	ds_read_b128 v[142:145], v201
	ds_read_b128 v[146:149], v202
	ds_read_b128 v[150:153], v203
	ds_read_b128 v[174:177], v204
	ds_read_b128 v[178:181], v205
	ds_read_b128 v[182:185], v206
	s_add_u32 s24, s4, vcc_lo
	s_addc_u32 s25, s5, vcc_hi
	s_add_u32 s24, s24, 0x100
	s_addc_u32 s25, s25, 0
	s_add_u32 s82, s39, vcc_lo
	s_addc_u32 s83, s67, vcc_hi
	s_cmpk_eq_i32 vcc_lo, 0x700
	s_cselect_b32 s87, s29, s83
	s_cselect_b32 s86, s38, s82
	s_cselect_b32 s83, s34, s25
	s_cselect_b32 s82, s35, s24
	v_lshl_add_u64 v[154:155], v[132:133], 0, vcc
	v_lshl_add_u64 v[250:251], v[154:155], 0, s[48:49]
	s_add_i32 m0, s79, 0x8000
	s_mov_b64 s[24:25], 0x20080
	ds_read_b128 v[218:221], v207
	ds_read_b128 v[222:225], v207 offset:2048
	ds_read_b128 v[226:229], v208
	ds_read_b128 v[230:233], v208 offset:2048
	ds_read_b128 v[234:237], v207 offset:4096
	ds_read_b128 v[238:241], v207 offset:6144
	ds_read_b128 v[242:245], v208 offset:4096
	ds_read_b128 v[246:249], v208 offset:6144
	global_load_lds_dwordx4 v[250:251], off
	v_lshl_add_u64 v[250:251], v[154:155], 0, s[24:25]
	s_add_i32 m0, s79, 0xa000
	s_mov_b64 s[24:25], 0x60080
	global_load_lds_dwordx4 v[250:251], off
	v_lshl_add_u64 v[250:251], v[154:155], 0, s[50:51]
	s_add_i32 m0, s79, 0xc000
	v_lshl_add_u64 v[154:155], v[154:155], 0, s[24:25]
	global_load_lds_dwordx4 v[250:251], off
	s_add_i32 m0, s79, 0xe000
	s_nop 0
	global_load_lds_dwordx4 v[154:155], off
	s_waitcnt vmcnt(8)
	s_waitcnt lgkmcnt(0)
	s_barrier
	v_mfma_f32_16x16x32_bf16 v[128:131], v[134:137], v[218:221], v[128:131]
	v_mfma_f32_16x16x32_bf16 v[128:131], v[138:141], v[226:229], v[128:131]
	v_mfma_f32_16x16x32_bf16 v[112:115], v[138:141], v[230:233], v[112:115]
	v_mfma_f32_16x16x32_bf16 v[112:115], v[134:137], v[222:225], v[112:115]
	v_mfma_f32_16x16x32_bf16 v[96:99], v[134:137], v[234:237], v[96:99]
	v_mfma_f32_16x16x32_bf16 v[96:99], v[138:141], v[242:245], v[96:99]
	v_mfma_f32_16x16x32_bf16 v[80:83], v[138:141], v[246:249], v[80:83]
	v_mfma_f32_16x16x32_bf16 v[80:83], v[134:137], v[238:241], v[80:83]
	v_mfma_f32_16x16x32_bf16 v[76:79], v[142:145], v[238:241], v[76:79]
	v_mfma_f32_16x16x32_bf16 v[76:79], v[146:149], v[246:249], v[76:79]
	v_mfma_f32_16x16x32_bf16 v[92:95], v[146:149], v[242:245], v[92:95]
	v_mfma_f32_16x16x32_bf16 v[92:95], v[142:145], v[234:237], v[92:95]
	v_mfma_f32_16x16x32_bf16 v[108:111], v[142:145], v[222:225], v[108:111]
	v_mfma_f32_16x16x32_bf16 v[108:111], v[146:149], v[230:233], v[108:111]
	v_mfma_f32_16x16x32_bf16 v[124:127], v[146:149], v[226:229], v[124:127]
	v_mfma_f32_16x16x32_bf16 v[124:127], v[142:145], v[218:221], v[124:127]
	v_mfma_f32_16x16x32_bf16 v[120:123], v[150:153], v[218:221], v[120:123]
	v_mfma_f32_16x16x32_bf16 v[120:123], v[174:177], v[226:229], v[120:123]
	v_mfma_f32_16x16x32_bf16 v[104:107], v[174:177], v[230:233], v[104:107]
	v_mfma_f32_16x16x32_bf16 v[104:107], v[150:153], v[222:225], v[104:107]
	v_mfma_f32_16x16x32_bf16 v[88:91], v[150:153], v[234:237], v[88:91]
	v_mfma_f32_16x16x32_bf16 v[88:91], v[174:177], v[242:245], v[88:91]
	v_mfma_f32_16x16x32_bf16 v[72:75], v[174:177], v[246:249], v[72:75]
	v_mfma_f32_16x16x32_bf16 v[72:75], v[150:153], v[238:241], v[72:75]
	v_mfma_f32_16x16x32_bf16 v[68:71], v[178:181], v[238:241], v[68:71]
	v_mfma_f32_16x16x32_bf16 v[68:71], v[182:185], v[246:249], v[68:71]
	v_mfma_f32_16x16x32_bf16 v[84:87], v[182:185], v[242:245], v[84:87]
	v_mfma_f32_16x16x32_bf16 v[84:87], v[178:181], v[234:237], v[84:87]
	v_mfma_f32_16x16x32_bf16 v[100:103], v[178:181], v[222:225], v[100:103]
	v_mfma_f32_16x16x32_bf16 v[100:103], v[182:185], v[230:233], v[100:103]
	v_mfma_f32_16x16x32_bf16 v[116:119], v[182:185], v[226:229], v[116:119]
	v_mfma_f32_16x16x32_bf16 v[116:119], v[178:181], v[218:221], v[116:119]
	s_barrier
	s_add_i32 s24, s1, s77
	v_lshl_add_u64 v[154:155], s[86:87], 0, v[158:159]
	s_mov_b32 m0, s24
	ds_read_b128 v[218:221], v207 offset:16384
	ds_read_b128 v[222:225], v207 offset:18432
	ds_read_b128 v[226:229], v208 offset:16384
	ds_read_b128 v[230:233], v208 offset:18432
	ds_read_b128 v[234:237], v207 offset:20480
	ds_read_b128 v[238:241], v207 offset:22528
	ds_read_b128 v[242:245], v208 offset:20480
	ds_read_b128 v[246:249], v208 offset:22528
	global_load_lds_dwordx4 v[154:155], off
	v_lshl_add_u64 v[250:251], v[154:155], 0, s[14:15]
	s_add_i32 m0, s24, 0x2000
	s_add_i32 s24, s12, s77
	global_load_lds_dwordx4 v[250:251], off
	v_lshl_add_u64 v[250:251], v[154:155], 0, s[16:17]
	s_mov_b32 m0, s24
	s_nop 0
	global_load_lds_dwordx4 v[250:251], off
	v_lshl_add_u64 v[250:251], v[154:155], 0, s[18:19]
	s_add_i32 m0, s24, 0x2000
	s_nop 0
	global_load_lds_dwordx4 v[250:251], off
	s_waitcnt vmcnt(4)
	s_waitcnt lgkmcnt(0)
	s_barrier
	v_mfma_f32_16x16x32_bf16 v[64:67], v[134:137], v[218:221], v[64:67]
	v_mfma_f32_16x16x32_bf16 v[64:67], v[138:141], v[226:229], v[64:67]
	v_mfma_f32_16x16x32_bf16 v[48:51], v[138:141], v[230:233], v[48:51]
	v_mfma_f32_16x16x32_bf16 v[48:51], v[134:137], v[222:225], v[48:51]
	v_mfma_f32_16x16x32_bf16 v[32:35], v[134:137], v[234:237], v[32:35]
	v_mfma_f32_16x16x32_bf16 v[32:35], v[138:141], v[242:245], v[32:35]
	v_mfma_f32_16x16x32_bf16 v[16:19], v[138:141], v[246:249], v[16:19]
	v_mfma_f32_16x16x32_bf16 v[16:19], v[134:137], v[238:241], v[16:19]
	v_mfma_f32_16x16x32_bf16 v[12:15], v[142:145], v[238:241], v[12:15]
	v_mfma_f32_16x16x32_bf16 v[12:15], v[146:149], v[246:249], v[12:15]
	v_mfma_f32_16x16x32_bf16 v[28:31], v[146:149], v[242:245], v[28:31]
	v_mfma_f32_16x16x32_bf16 v[28:31], v[142:145], v[234:237], v[28:31]
	v_mfma_f32_16x16x32_bf16 v[44:47], v[142:145], v[222:225], v[44:47]
	v_mfma_f32_16x16x32_bf16 v[44:47], v[146:149], v[230:233], v[44:47]
	v_mfma_f32_16x16x32_bf16 v[60:63], v[146:149], v[226:229], v[60:63]
	v_mfma_f32_16x16x32_bf16 v[60:63], v[142:145], v[218:221], v[60:63]
	v_mfma_f32_16x16x32_bf16 v[56:59], v[150:153], v[218:221], v[56:59]
	v_mfma_f32_16x16x32_bf16 v[56:59], v[174:177], v[226:229], v[56:59]
	v_mfma_f32_16x16x32_bf16 v[40:43], v[174:177], v[230:233], v[40:43]
	v_mfma_f32_16x16x32_bf16 v[40:43], v[150:153], v[222:225], v[40:43]
	v_mfma_f32_16x16x32_bf16 v[24:27], v[150:153], v[234:237], v[24:27]
	v_mfma_f32_16x16x32_bf16 v[24:27], v[174:177], v[242:245], v[24:27]
	v_mfma_f32_16x16x32_bf16 v[8:11], v[174:177], v[246:249], v[8:11]
	v_mfma_f32_16x16x32_bf16 v[8:11], v[150:153], v[238:241], v[8:11]
	v_mfma_f32_16x16x32_bf16 v[4:7], v[178:181], v[238:241], v[4:7]
	v_mfma_f32_16x16x32_bf16 v[4:7], v[182:185], v[246:249], v[4:7]
	v_mfma_f32_16x16x32_bf16 v[20:23], v[182:185], v[242:245], v[20:23]
	v_mfma_f32_16x16x32_bf16 v[20:23], v[178:181], v[234:237], v[20:23]
	v_mfma_f32_16x16x32_bf16 v[36:39], v[178:181], v[222:225], v[36:39]
	v_mfma_f32_16x16x32_bf16 v[36:39], v[182:185], v[230:233], v[36:39]
	v_mfma_f32_16x16x32_bf16 v[52:55], v[182:185], v[226:229], v[52:55]
	v_mfma_f32_16x16x32_bf16 v[52:55], v[178:181], v[218:221], v[52:55]
	s_barrier
	ds_read_b128 v[134:137], v213
	ds_read_b128 v[138:141], v214
	ds_read_b128 v[142:145], v209
	ds_read_b128 v[146:149], v210
	ds_read_b128 v[150:153], v215
	ds_read_b128 v[174:177], v216
	ds_read_b128 v[178:181], v211
	ds_read_b128 v[182:185], v212
	s_mov_b32 m0, s79
	v_lshl_add_u64 v[250:251], s[82:83], 0, v[0:1]
	ds_read_b128 v[218:221], v207 offset:32768
	ds_read_b128 v[222:225], v207 offset:34816
	ds_read_b128 v[226:229], v208 offset:32768
	ds_read_b128 v[230:233], v208 offset:34816
	ds_read_b128 v[234:237], v207 offset:36864
	ds_read_b128 v[238:241], v207 offset:38912
	ds_read_b128 v[242:245], v208 offset:36864
	ds_read_b128 v[246:249], v208 offset:38912
	global_load_lds_dwordx4 v[250:251], off
	v_lshl_add_u64 v[252:253], v[250:251], 0, s[20:21]
	s_mov_b32 m0, s81
	s_nop 0
	global_load_lds_dwordx4 v[252:253], off
	v_lshl_add_u64 v[252:253], v[250:251], 0, s[14:15]
	s_mov_b32 m0, s97
	v_lshl_add_u64 v[250:251], v[250:251], 0, s[22:23]
	global_load_lds_dwordx4 v[252:253], off
	s_mov_b32 m0, s64
	s_nop 0
	global_load_lds_dwordx4 v[250:251], off
	s_waitcnt vmcnt(8)
	s_waitcnt lgkmcnt(0)
	s_barrier
	v_mfma_f32_16x16x32_bf16 v[128:131], v[134:137], v[218:221], v[128:131]
	v_mfma_f32_16x16x32_bf16 v[128:131], v[138:141], v[226:229], v[128:131]
	v_mfma_f32_16x16x32_bf16 v[112:115], v[138:141], v[230:233], v[112:115]
	v_mfma_f32_16x16x32_bf16 v[112:115], v[134:137], v[222:225], v[112:115]
	v_mfma_f32_16x16x32_bf16 v[96:99], v[134:137], v[234:237], v[96:99]
	v_mfma_f32_16x16x32_bf16 v[96:99], v[138:141], v[242:245], v[96:99]
	v_mfma_f32_16x16x32_bf16 v[80:83], v[138:141], v[246:249], v[80:83]
	v_mfma_f32_16x16x32_bf16 v[80:83], v[134:137], v[238:241], v[80:83]
	v_mfma_f32_16x16x32_bf16 v[76:79], v[142:145], v[238:241], v[76:79]
	v_mfma_f32_16x16x32_bf16 v[76:79], v[146:149], v[246:249], v[76:79]
	v_mfma_f32_16x16x32_bf16 v[92:95], v[146:149], v[242:245], v[92:95]
	v_mfma_f32_16x16x32_bf16 v[92:95], v[142:145], v[234:237], v[92:95]
	v_mfma_f32_16x16x32_bf16 v[108:111], v[142:145], v[222:225], v[108:111]
	v_mfma_f32_16x16x32_bf16 v[108:111], v[146:149], v[230:233], v[108:111]
	v_mfma_f32_16x16x32_bf16 v[124:127], v[146:149], v[226:229], v[124:127]
	v_mfma_f32_16x16x32_bf16 v[124:127], v[142:145], v[218:221], v[124:127]
	v_mfma_f32_16x16x32_bf16 v[120:123], v[150:153], v[218:221], v[120:123]
	v_mfma_f32_16x16x32_bf16 v[120:123], v[174:177], v[226:229], v[120:123]
	v_mfma_f32_16x16x32_bf16 v[104:107], v[174:177], v[230:233], v[104:107]
	v_mfma_f32_16x16x32_bf16 v[104:107], v[150:153], v[222:225], v[104:107]
	v_mfma_f32_16x16x32_bf16 v[88:91], v[150:153], v[234:237], v[88:91]
	v_mfma_f32_16x16x32_bf16 v[88:91], v[174:177], v[242:245], v[88:91]
	v_mfma_f32_16x16x32_bf16 v[72:75], v[174:177], v[246:249], v[72:75]
	v_mfma_f32_16x16x32_bf16 v[72:75], v[150:153], v[238:241], v[72:75]
	v_mfma_f32_16x16x32_bf16 v[68:71], v[178:181], v[238:241], v[68:71]
	v_mfma_f32_16x16x32_bf16 v[68:71], v[182:185], v[246:249], v[68:71]
	v_mfma_f32_16x16x32_bf16 v[84:87], v[182:185], v[242:245], v[84:87]
	v_mfma_f32_16x16x32_bf16 v[84:87], v[178:181], v[234:237], v[84:87]
	v_mfma_f32_16x16x32_bf16 v[100:103], v[178:181], v[222:225], v[100:103]
	v_mfma_f32_16x16x32_bf16 v[100:103], v[182:185], v[230:233], v[100:103]
	v_mfma_f32_16x16x32_bf16 v[116:119], v[182:185], v[226:229], v[116:119]
	v_mfma_f32_16x16x32_bf16 v[116:119], v[178:181], v[218:221], v[116:119]
	s_barrier
	s_add_i32 s24, s70, s77
	v_lshl_add_u64 v[250:251], v[154:155], 0, s[48:49]
	s_mov_b32 m0, s24
	ds_read_b128 v[218:221], v207 offset:49152
	ds_read_b128 v[222:225], v207 offset:51200
	ds_read_b128 v[226:229], v208 offset:49152
	ds_read_b128 v[230:233], v208 offset:51200
	ds_read_b128 v[234:237], v207 offset:53248
	ds_read_b128 v[238:241], v207 offset:55296
	ds_read_b128 v[242:245], v208 offset:53248
	ds_read_b128 v[246:249], v208 offset:55296
	global_load_lds_dwordx4 v[250:251], off
	v_lshl_add_u64 v[250:251], v[154:155], 0, s[50:51]
	s_add_i32 m0, s24, 0x2000
	s_add_i32 s24, s71, s77
	global_load_lds_dwordx4 v[250:251], off
	v_lshl_add_u64 v[250:251], v[154:155], 0, s[52:53]
	s_mov_b32 m0, s24
	v_lshl_add_u64 v[154:155], v[154:155], 0, s[54:55]
	global_load_lds_dwordx4 v[250:251], off
	s_add_i32 m0, s24, 0x2000
	s_nop 0
	global_load_lds_dwordx4 v[154:155], off
	s_waitcnt vmcnt(4)
	s_waitcnt lgkmcnt(0)
	s_barrier
	v_mfma_f32_16x16x32_bf16 v[64:67], v[134:137], v[218:221], v[64:67]
	v_mfma_f32_16x16x32_bf16 v[64:67], v[138:141], v[226:229], v[64:67]
	v_mfma_f32_16x16x32_bf16 v[48:51], v[138:141], v[230:233], v[48:51]
	v_mfma_f32_16x16x32_bf16 v[48:51], v[134:137], v[222:225], v[48:51]
	v_mfma_f32_16x16x32_bf16 v[32:35], v[134:137], v[234:237], v[32:35]
	v_mfma_f32_16x16x32_bf16 v[32:35], v[138:141], v[242:245], v[32:35]
	v_mfma_f32_16x16x32_bf16 v[16:19], v[138:141], v[246:249], v[16:19]
	v_mfma_f32_16x16x32_bf16 v[16:19], v[134:137], v[238:241], v[16:19]
	v_mfma_f32_16x16x32_bf16 v[12:15], v[142:145], v[238:241], v[12:15]
	v_mfma_f32_16x16x32_bf16 v[12:15], v[146:149], v[246:249], v[12:15]
	v_mfma_f32_16x16x32_bf16 v[28:31], v[146:149], v[242:245], v[28:31]
	v_mfma_f32_16x16x32_bf16 v[28:31], v[142:145], v[234:237], v[28:31]
	v_mfma_f32_16x16x32_bf16 v[44:47], v[142:145], v[222:225], v[44:47]
	v_mfma_f32_16x16x32_bf16 v[44:47], v[146:149], v[230:233], v[44:47]
	v_mfma_f32_16x16x32_bf16 v[60:63], v[146:149], v[226:229], v[60:63]
	v_mfma_f32_16x16x32_bf16 v[60:63], v[142:145], v[218:221], v[60:63]
	v_mfma_f32_16x16x32_bf16 v[56:59], v[150:153], v[218:221], v[56:59]
	v_mfma_f32_16x16x32_bf16 v[56:59], v[174:177], v[226:229], v[56:59]
	v_mfma_f32_16x16x32_bf16 v[40:43], v[174:177], v[230:233], v[40:43]
	v_mfma_f32_16x16x32_bf16 v[40:43], v[150:153], v[222:225], v[40:43]
	v_mfma_f32_16x16x32_bf16 v[24:27], v[150:153], v[234:237], v[24:27]
	v_mfma_f32_16x16x32_bf16 v[24:27], v[174:177], v[242:245], v[24:27]
	v_mfma_f32_16x16x32_bf16 v[8:11], v[174:177], v[246:249], v[8:11]
	v_mfma_f32_16x16x32_bf16 v[8:11], v[150:153], v[238:241], v[8:11]
	v_mfma_f32_16x16x32_bf16 v[4:7], v[178:181], v[238:241], v[4:7]
	v_mfma_f32_16x16x32_bf16 v[4:7], v[182:185], v[246:249], v[4:7]
	v_mfma_f32_16x16x32_bf16 v[20:23], v[182:185], v[242:245], v[20:23]
	v_mfma_f32_16x16x32_bf16 v[20:23], v[178:181], v[234:237], v[20:23]
	v_mfma_f32_16x16x32_bf16 v[36:39], v[178:181], v[222:225], v[36:39]
	v_mfma_f32_16x16x32_bf16 v[36:39], v[182:185], v[230:233], v[36:39]
	v_mfma_f32_16x16x32_bf16 v[52:55], v[182:185], v[226:229], v[52:55]
	v_mfma_f32_16x16x32_bf16 v[52:55], v[178:181], v[218:221], v[52:55]
	s_barrier
	s_add_i32 s94, s94, 2
	s_add_u32 vcc_lo, vcc_lo, 0x100
	s_addc_u32 vcc_hi, vcc_hi, 0
	s_cmp_gt_u32 s94, 13
	s_cbranch_scc0 .LBB0_384
	s_andn2_b64 vcc, s[56:57], s[8:9]
	s_cbranch_vccz .LBB0_387
	s_barrier
.LBB0_387:
	s_lshl_b32 s29, s80, 8
	s_add_i32 s29, s29, s65
	v_or_b32_e32 v174, s29, v3
	s_cmp_gt_i32 s96, 13
	s_mov_b64 s[4:5], -1
	s_cbranch_scc0 .LBB0_390
	v_lshl_add_u32 v160, s96, 7, v198
	v_and_b32_e32 v140, 0xff, v198
	v_lshlrev_b32_e32 v140, 2, v140
	v_add_u32_e32 v140, 0x21000, v140
	v_add_u32_e32 v140, s99, v140
	ds_read_b128 v[136:139], v140 offset:16
	ds_read_b128 v[144:147], v140
	ds_read_b128 v[132:135], v140 offset:528
	ds_read_b128 v[140:143], v140 offset:512
	v_ashrrev_i32_e32 v175, 31, v174
	v_lshlrev_b64 v[148:149], 10, v[174:175]
	v_lshl_add_u64 v[148:149], v[148:149], 0, v[160:161]
	v_lshlrev_b64 v[148:149], 1, v[148:149]
	s_mov_b64 s[4:5], 0x48000
	s_waitcnt lgkmcnt(0)
	v_add_f32_e32 v150, v128, v144
	v_mul_f32_e32 v150, 0xbfb8aa3b, v150
	v_exp_f32_e32 v150, v150
	v_add_f32_e32 v176, v123, v143
	v_mul_f32_e32 v176, 0xbfb8aa3b, v176
	v_exp_f32_e32 v176, v176
	v_add_f32_e32 v151, 1.0, v150
	v_add_f32_e32 v150, v120, v140
	v_mul_f32_e32 v150, 0xbfb8aa3b, v150
	v_exp_f32_e32 v150, v150
	v_rcp_f32_e32 v151, v151
	v_add_f32_e32 v176, 1.0, v176
	v_rcp_f32_e32 v182, v176
	v_add_f32_e32 v152, 1.0, v150
	v_rcp_f32_e32 v150, v152
	v_mul_f32_e32 v151, v152, v151
	v_add_f32_e32 v152, v129, v145
	v_mul_f32_e32 v152, 0xbfb8aa3b, v152
	v_exp_f32_e32 v152, v152
	v_add_f32_e32 v177, v116, v132
	v_mul_f32_e32 v177, 0xbfb8aa3b, v177
	v_exp_f32_e32 v177, v177
	v_add_f32_e32 v153, 1.0, v152
	v_add_f32_e32 v152, v121, v141
	v_mul_f32_e32 v152, 0xbfb8aa3b, v152
	v_exp_f32_e32 v152, v152
	v_rcp_f32_e32 v153, v153
	v_add_f32_e32 v177, 1.0, v177
	v_rcp_f32_e32 v183, v177
	v_add_f32_e32 v154, 1.0, v152
	v_rcp_f32_e32 v152, v154
	v_mul_f32_e32 v153, v154, v153
	v_add_f32_e32 v154, v130, v146
	v_mul_f32_e32 v154, 0xbfb8aa3b, v154
	v_exp_f32_e32 v154, v154
	s_nop 0
	v_add_f32_e32 v155, 1.0, v154
	v_add_f32_e32 v154, v122, v142
	v_mul_f32_e32 v154, 0xbfb8aa3b, v154
	v_exp_f32_e32 v154, v154
	v_rcp_f32_e32 v155, v155
	v_add_f32_e32 v175, 1.0, v154
	v_rcp_f32_e32 v154, v175
	v_mul_f32_e32 v155, v175, v155
	v_add_f32_e32 v175, v131, v147
	v_mul_f32_e32 v175, 0xbfb8aa3b, v175
	v_exp_f32_e32 v175, v175
	s_nop 0
	v_add_f32_e32 v175, 1.0, v175
	v_rcp_f32_e32 v175, v175
	s_nop 0
	v_mul_f32_e32 v175, v176, v175
	v_add_f32_e32 v176, v124, v136
	v_mul_f32_e32 v176, 0xbfb8aa3b, v176
	v_exp_f32_e32 v176, v176
	s_nop 0
	v_add_f32_e32 v176, 1.0, v176
	v_rcp_f32_e32 v176, v176
	s_nop 0
	v_mul_f32_e32 v178, v177, v176
	v_add_f32_e32 v176, v125, v137
	v_mul_f32_e32 v176, 0xbfb8aa3b, v176
	v_exp_f32_e32 v176, v176
	v_add_f32_e32 v177, v117, v133
	v_mul_f32_e32 v177, 0xbfb8aa3b, v177
	v_exp_f32_e32 v177, v177
	v_add_f32_e32 v176, 1.0, v176
	v_rcp_f32_e32 v176, v176
	v_add_f32_e32 v177, 1.0, v177
	v_rcp_f32_e32 v184, v177
	v_mul_f32_e32 v179, v177, v176
	v_add_f32_e32 v176, v126, v138
	v_mul_f32_e32 v176, 0xbfb8aa3b, v176
	v_exp_f32_e32 v176, v176
	v_add_f32_e32 v177, v118, v134
	v_mul_f32_e32 v177, 0xbfb8aa3b, v177
	v_exp_f32_e32 v177, v177
	v_add_f32_e32 v176, 1.0, v176
	v_rcp_f32_e32 v176, v176
	v_add_f32_e32 v177, 1.0, v177
	v_rcp_f32_e32 v185, v177
	v_mul_f32_e32 v180, v177, v176
	v_add_f32_e32 v176, v127, v139
	v_mul_f32_e32 v176, 0xbfb8aa3b, v176
	v_exp_f32_e32 v176, v176
	v_add_f32_e32 v177, v119, v135
	v_mul_f32_e32 v177, 0xbfb8aa3b, v177
	v_exp_f32_e32 v177, v177
	v_add_f32_e32 v176, 1.0, v176
	v_rcp_f32_e32 v176, v176
	v_add_f32_e32 v177, 1.0, v177
	v_rcp_f32_e32 v217, v177
	v_mul_f32_e32 v181, v177, v176
	v_cvt_pk_bf16_f32 v176, v151, v153
	v_cvt_pk_bf16_f32 v177, v155, v175
	v_cvt_pk_bf16_f32 v178, v178, v179
	v_cvt_pk_bf16_f32 v179, v180, v181
	v_lshl_add_u64 v[180:181], s[44:45], 0, v[148:149]
	global_store_dwordx4 v[180:181], v[176:179], off
	v_cvt_pk_bf16_f32 v150, v150, v152
	v_cvt_pk_bf16_f32 v151, v154, v182
	v_cvt_pk_bf16_f32 v152, v183, v184
	v_lshl_add_u64 v[154:155], s[46:47], 0, v[148:149]
	v_cvt_pk_bf16_f32 v153, v185, v217
	global_store_dwordx4 v[154:155], v[150:153], off
	v_add_f32_e32 v154, v105, v141
	v_mul_f32_e32 v154, 0xbfb8aa3b, v154
	v_add_f32_e32 v152, v112, v144
	v_mul_f32_e32 v152, 0xbfb8aa3b, v152
	v_exp_f32_e32 v152, v152
	v_add_f32_e32 v153, v104, v140
	v_mul_f32_e32 v153, 0xbfb8aa3b, v153
	v_exp_f32_e32 v153, v153
	v_add_f32_e32 v152, 1.0, v152
	v_rcp_f32_e32 v152, v152
	v_exp_f32_e32 v154, v154
	v_add_f32_e32 v153, 1.0, v153
	v_rcp_f32_e32 v175, v153
	v_mul_f32_e32 v152, v153, v152
	v_add_f32_e32 v153, v113, v145
	v_mul_f32_e32 v153, 0xbfb8aa3b, v153
	v_exp_f32_e32 v153, v153
	v_add_f32_e32 v154, 1.0, v154
	v_rcp_f32_e32 v178, v154
	v_add_f32_e32 v155, v106, v142
	v_add_f32_e32 v153, 1.0, v153
	v_rcp_f32_e32 v153, v153
	v_mul_f32_e32 v155, 0xbfb8aa3b, v155
	v_exp_f32_e32 v155, v155
	v_or_b32_e32 v150, 16, v174
	v_mul_f32_e32 v153, v154, v153
	v_add_f32_e32 v154, v114, v146
	v_mul_f32_e32 v154, 0xbfb8aa3b, v154
	v_exp_f32_e32 v154, v154
	v_add_f32_e32 v155, 1.0, v155
	v_rcp_f32_e32 v179, v155
	v_ashrrev_i32_e32 v151, 31, v150
	v_add_f32_e32 v154, 1.0, v154
	v_rcp_f32_e32 v154, v154
	v_lshlrev_b64 v[150:151], 10, v[150:151]
	v_mul_f32_e32 v176, v155, v154
	v_add_f32_e32 v154, v115, v147
	v_mul_f32_e32 v154, 0xbfb8aa3b, v154
	v_exp_f32_e32 v154, v154
	v_add_f32_e32 v155, v107, v143
	v_mul_f32_e32 v155, 0xbfb8aa3b, v155
	v_exp_f32_e32 v155, v155
	v_add_f32_e32 v154, 1.0, v154
	v_rcp_f32_e32 v154, v154
	v_add_f32_e32 v155, 1.0, v155
	v_rcp_f32_e32 v180, v155
	v_mul_f32_e32 v177, v155, v154
	v_add_f32_e32 v154, v108, v136
	v_mul_f32_e32 v154, 0xbfb8aa3b, v154
	v_exp_f32_e32 v154, v154
	v_add_f32_e32 v155, v100, v132
	v_mul_f32_e32 v155, 0xbfb8aa3b, v155
	v_exp_f32_e32 v155, v155
	v_add_f32_e32 v154, 1.0, v154
	v_rcp_f32_e32 v154, v154
	v_add_f32_e32 v155, 1.0, v155
	v_rcp_f32_e32 v181, v155
	v_mul_f32_e32 v182, v155, v154
	v_add_f32_e32 v154, v109, v137
	v_mul_f32_e32 v154, 0xbfb8aa3b, v154
	v_exp_f32_e32 v154, v154
	v_add_f32_e32 v155, v101, v133
	v_mul_f32_e32 v155, 0xbfb8aa3b, v155
	v_exp_f32_e32 v155, v155
	v_add_f32_e32 v154, 1.0, v154
	v_rcp_f32_e32 v154, v154
	v_add_f32_e32 v155, 1.0, v155
	v_rcp_f32_e32 v183, v155
	v_mul_f32_e32 v184, v155, v154
	v_add_f32_e32 v154, v110, v138
	v_mul_f32_e32 v154, 0xbfb8aa3b, v154
	v_exp_f32_e32 v154, v154
	v_add_f32_e32 v155, v102, v134
	v_mul_f32_e32 v155, 0xbfb8aa3b, v155
	v_exp_f32_e32 v155, v155
	v_add_f32_e32 v154, 1.0, v154
	v_rcp_f32_e32 v154, v154
	v_add_f32_e32 v155, 1.0, v155
	v_rcp_f32_e32 v185, v155
	v_mul_f32_e32 v217, v155, v154
	v_add_f32_e32 v154, v111, v139
	v_mul_f32_e32 v154, 0xbfb8aa3b, v154
	v_exp_f32_e32 v154, v154
	v_add_f32_e32 v155, v103, v135
	v_mul_f32_e32 v155, 0xbfb8aa3b, v155
	v_exp_f32_e32 v155, v155
	v_add_f32_e32 v154, 1.0, v154
	v_rcp_f32_e32 v154, v154
	v_add_f32_e32 v155, 1.0, v155
	v_rcp_f32_e32 v218, v155
	v_mul_f32_e32 v219, v155, v154
	v_lshl_add_u64 v[154:155], v[150:151], 0, v[160:161]
	v_lshlrev_b64 v[154:155], 1, v[154:155]
	v_cvt_pk_bf16_f32 v150, v152, v153
	v_cvt_pk_bf16_f32 v151, v176, v177
	v_cvt_pk_bf16_f32 v152, v182, v184
	v_lshl_add_u64 v[176:177], s[44:45], 0, v[154:155]
	v_cvt_pk_bf16_f32 v153, v217, v219
	global_store_dwordx4 v[176:177], v[150:153], off
	v_lshl_add_u64 v[154:155], s[46:47], 0, v[154:155]
	s_nop 0
	v_cvt_pk_bf16_f32 v150, v175, v178
	v_cvt_pk_bf16_f32 v151, v179, v180
	v_cvt_pk_bf16_f32 v152, v181, v183
	v_cvt_pk_bf16_f32 v153, v185, v218
	global_store_dwordx4 v[154:155], v[150:153], off
	v_add_f32_e32 v154, v89, v141
	v_mul_f32_e32 v154, 0xbfb8aa3b, v154
	v_add_f32_e32 v152, v96, v144
	v_mul_f32_e32 v152, 0xbfb8aa3b, v152
	v_exp_f32_e32 v152, v152
	v_add_f32_e32 v153, v88, v140
	v_mul_f32_e32 v153, 0xbfb8aa3b, v153
	v_exp_f32_e32 v153, v153
	v_add_f32_e32 v152, 1.0, v152
	v_rcp_f32_e32 v152, v152
	v_exp_f32_e32 v154, v154
	v_add_f32_e32 v153, 1.0, v153
	v_rcp_f32_e32 v175, v153
	v_mul_f32_e32 v152, v153, v152
	v_add_f32_e32 v153, v97, v145
	v_mul_f32_e32 v153, 0xbfb8aa3b, v153
	v_exp_f32_e32 v153, v153
	v_add_f32_e32 v154, 1.0, v154
	v_rcp_f32_e32 v178, v154
	v_add_f32_e32 v155, v90, v142
	v_add_f32_e32 v153, 1.0, v153
	v_rcp_f32_e32 v153, v153
	v_mul_f32_e32 v155, 0xbfb8aa3b, v155
	v_exp_f32_e32 v155, v155
	v_or_b32_e32 v150, 32, v174
	v_mul_f32_e32 v153, v154, v153
	v_add_f32_e32 v154, v98, v146
	v_mul_f32_e32 v154, 0xbfb8aa3b, v154
	v_exp_f32_e32 v154, v154
	v_add_f32_e32 v155, 1.0, v155
	v_rcp_f32_e32 v179, v155
	v_ashrrev_i32_e32 v151, 31, v150
	v_add_f32_e32 v154, 1.0, v154
	v_rcp_f32_e32 v154, v154
	v_lshlrev_b64 v[150:151], 10, v[150:151]
	v_mul_f32_e32 v176, v155, v154
	v_add_f32_e32 v154, v99, v147
	v_mul_f32_e32 v154, 0xbfb8aa3b, v154
	v_exp_f32_e32 v154, v154
	v_add_f32_e32 v155, v91, v143
	v_mul_f32_e32 v155, 0xbfb8aa3b, v155
	v_exp_f32_e32 v155, v155
	v_add_f32_e32 v154, 1.0, v154
	v_rcp_f32_e32 v154, v154
	v_add_f32_e32 v155, 1.0, v155
	v_rcp_f32_e32 v180, v155
	v_mul_f32_e32 v177, v155, v154
	v_add_f32_e32 v154, v92, v136
	v_mul_f32_e32 v154, 0xbfb8aa3b, v154
	v_exp_f32_e32 v154, v154
	v_add_f32_e32 v155, v84, v132
	v_mul_f32_e32 v155, 0xbfb8aa3b, v155
	v_exp_f32_e32 v155, v155
	v_add_f32_e32 v154, 1.0, v154
	v_rcp_f32_e32 v154, v154
	v_add_f32_e32 v155, 1.0, v155
	v_rcp_f32_e32 v181, v155
	v_mul_f32_e32 v182, v155, v154
	v_add_f32_e32 v154, v93, v137
	v_mul_f32_e32 v154, 0xbfb8aa3b, v154
	v_exp_f32_e32 v154, v154
	v_add_f32_e32 v155, v85, v133
	v_mul_f32_e32 v155, 0xbfb8aa3b, v155
	v_exp_f32_e32 v155, v155
	v_add_f32_e32 v154, 1.0, v154
	v_rcp_f32_e32 v154, v154
	v_add_f32_e32 v155, 1.0, v155
	v_rcp_f32_e32 v183, v155
	v_mul_f32_e32 v184, v155, v154
	v_add_f32_e32 v154, v94, v138
	v_mul_f32_e32 v154, 0xbfb8aa3b, v154
	v_exp_f32_e32 v154, v154
	v_add_f32_e32 v155, v86, v134
	v_mul_f32_e32 v155, 0xbfb8aa3b, v155
	v_exp_f32_e32 v155, v155
	v_add_f32_e32 v154, 1.0, v154
	v_rcp_f32_e32 v154, v154
	v_add_f32_e32 v155, 1.0, v155
	v_rcp_f32_e32 v185, v155
	v_mul_f32_e32 v217, v155, v154
	v_add_f32_e32 v154, v95, v139
	v_mul_f32_e32 v154, 0xbfb8aa3b, v154
	v_exp_f32_e32 v154, v154
	v_add_f32_e32 v155, v87, v135
	v_mul_f32_e32 v155, 0xbfb8aa3b, v155
	v_exp_f32_e32 v155, v155
	v_add_f32_e32 v154, 1.0, v154
	v_rcp_f32_e32 v154, v154
	v_add_f32_e32 v155, 1.0, v155
	v_rcp_f32_e32 v218, v155
	v_mul_f32_e32 v219, v155, v154
	v_lshl_add_u64 v[154:155], v[150:151], 0, v[160:161]
	v_lshlrev_b64 v[154:155], 1, v[154:155]
	v_cvt_pk_bf16_f32 v150, v152, v153
	v_cvt_pk_bf16_f32 v151, v176, v177
	v_cvt_pk_bf16_f32 v152, v182, v184
	v_lshl_add_u64 v[176:177], s[44:45], 0, v[154:155]
	v_cvt_pk_bf16_f32 v153, v217, v219
	global_store_dwordx4 v[176:177], v[150:153], off
	v_lshl_add_u64 v[154:155], s[46:47], 0, v[154:155]
	s_nop 0
	v_cvt_pk_bf16_f32 v150, v175, v178
	v_cvt_pk_bf16_f32 v151, v179, v180
	v_cvt_pk_bf16_f32 v152, v181, v183
	v_cvt_pk_bf16_f32 v153, v185, v218
	global_store_dwordx4 v[154:155], v[150:153], off
	v_add_f32_e32 v154, v73, v141
	v_mul_f32_e32 v154, 0xbfb8aa3b, v154
	v_add_f32_e32 v152, v80, v144
	v_mul_f32_e32 v152, 0xbfb8aa3b, v152
	v_exp_f32_e32 v152, v152
	v_add_f32_e32 v153, v72, v140
	v_mul_f32_e32 v153, 0xbfb8aa3b, v153
	v_exp_f32_e32 v153, v153
	v_add_f32_e32 v152, 1.0, v152
	v_rcp_f32_e32 v152, v152
	v_exp_f32_e32 v154, v154
	v_add_f32_e32 v153, 1.0, v153
	v_rcp_f32_e32 v175, v153
	v_mul_f32_e32 v152, v153, v152
	v_add_f32_e32 v153, v81, v145
	v_mul_f32_e32 v153, 0xbfb8aa3b, v153
	v_exp_f32_e32 v153, v153
	v_add_f32_e32 v154, 1.0, v154
	v_rcp_f32_e32 v178, v154
	v_add_f32_e32 v155, v74, v142
	v_add_f32_e32 v153, 1.0, v153
	v_rcp_f32_e32 v153, v153
	v_mul_f32_e32 v155, 0xbfb8aa3b, v155
	v_exp_f32_e32 v155, v155
	v_or_b32_e32 v150, 48, v174
	v_mul_f32_e32 v153, v154, v153
	v_add_f32_e32 v154, v82, v146
	v_mul_f32_e32 v154, 0xbfb8aa3b, v154
	v_exp_f32_e32 v154, v154
	v_add_f32_e32 v155, 1.0, v155
	v_rcp_f32_e32 v179, v155
	v_ashrrev_i32_e32 v151, 31, v150
	v_add_f32_e32 v154, 1.0, v154
	v_rcp_f32_e32 v154, v154
	v_lshlrev_b64 v[150:151], 10, v[150:151]
	v_mul_f32_e32 v176, v155, v154
	v_add_f32_e32 v154, v83, v147
	v_mul_f32_e32 v154, 0xbfb8aa3b, v154
	v_exp_f32_e32 v154, v154
	v_add_f32_e32 v155, v75, v143
	v_mul_f32_e32 v155, 0xbfb8aa3b, v155
	v_exp_f32_e32 v155, v155
	v_add_f32_e32 v154, 1.0, v154
	v_rcp_f32_e32 v154, v154
	v_add_f32_e32 v155, 1.0, v155
	v_rcp_f32_e32 v180, v155
	v_mul_f32_e32 v177, v155, v154
	v_add_f32_e32 v154, v76, v136
	v_mul_f32_e32 v154, 0xbfb8aa3b, v154
	v_exp_f32_e32 v154, v154
	v_add_f32_e32 v155, v68, v132
	v_mul_f32_e32 v155, 0xbfb8aa3b, v155
	v_exp_f32_e32 v155, v155
	v_add_f32_e32 v154, 1.0, v154
	v_rcp_f32_e32 v154, v154
	v_add_f32_e32 v155, 1.0, v155
	v_rcp_f32_e32 v181, v155
	v_mul_f32_e32 v182, v155, v154
	v_add_f32_e32 v154, v77, v137
	v_mul_f32_e32 v154, 0xbfb8aa3b, v154
	v_exp_f32_e32 v154, v154
	v_add_f32_e32 v155, v69, v133
	v_mul_f32_e32 v155, 0xbfb8aa3b, v155
	v_exp_f32_e32 v155, v155
	v_add_f32_e32 v154, 1.0, v154
	v_rcp_f32_e32 v154, v154
	v_add_f32_e32 v155, 1.0, v155
	v_rcp_f32_e32 v183, v155
	v_mul_f32_e32 v184, v155, v154
	v_add_f32_e32 v154, v78, v138
	v_mul_f32_e32 v154, 0xbfb8aa3b, v154
	v_exp_f32_e32 v154, v154
	v_add_f32_e32 v155, v70, v134
	v_mul_f32_e32 v155, 0xbfb8aa3b, v155
	v_exp_f32_e32 v155, v155
	v_add_f32_e32 v154, 1.0, v154
	v_rcp_f32_e32 v154, v154
	v_add_f32_e32 v155, 1.0, v155
	v_rcp_f32_e32 v185, v155
	v_mul_f32_e32 v217, v155, v154
	v_add_f32_e32 v154, v79, v139
	v_mul_f32_e32 v154, 0xbfb8aa3b, v154
	v_exp_f32_e32 v154, v154
	v_add_f32_e32 v155, v71, v135
	v_mul_f32_e32 v155, 0xbfb8aa3b, v155
	v_exp_f32_e32 v155, v155
	v_add_f32_e32 v154, 1.0, v154
	v_rcp_f32_e32 v154, v154
	v_add_f32_e32 v155, 1.0, v155
	v_rcp_f32_e32 v218, v155
	v_mul_f32_e32 v219, v155, v154
	v_lshl_add_u64 v[154:155], v[150:151], 0, v[160:161]
	v_lshlrev_b64 v[154:155], 1, v[154:155]
	v_cvt_pk_bf16_f32 v150, v152, v153
	v_cvt_pk_bf16_f32 v151, v176, v177
	v_lshl_add_u64 v[176:177], s[44:45], 0, v[154:155]
	v_cvt_pk_bf16_f32 v152, v182, v184
	v_cvt_pk_bf16_f32 v153, v217, v219
	global_store_dwordx4 v[176:177], v[150:153], off
	v_lshl_add_u64 v[154:155], s[46:47], 0, v[154:155]
	v_add_f32_e32 v176, v53, v133
	v_cvt_pk_bf16_f32 v150, v175, v178
	v_cvt_pk_bf16_f32 v151, v179, v180
	v_cvt_pk_bf16_f32 v152, v181, v183
	v_cvt_pk_bf16_f32 v153, v185, v218
	global_store_dwordx4 v[154:155], v[150:153], off
	v_add_f32_e32 v154, v59, v143
	v_mul_f32_e32 v154, 0xbfb8aa3b, v154
	v_add_f32_e32 v150, v64, v144
	v_mul_f32_e32 v150, 0xbfb8aa3b, v150
	v_exp_f32_e32 v150, v150
	v_add_f32_e32 v151, v56, v140
	v_mul_f32_e32 v151, 0xbfb8aa3b, v151
	v_exp_f32_e32 v151, v151
	v_add_f32_e32 v150, 1.0, v150
	v_rcp_f32_e32 v150, v150
	v_add_f32_e32 v152, v57, v141
	v_add_f32_e32 v151, 1.0, v151
	v_rcp_f32_e32 v160, v151
	v_mul_f32_e32 v150, v151, v150
	v_add_f32_e32 v151, v65, v145
	v_mul_f32_e32 v151, 0xbfb8aa3b, v151
	v_exp_f32_e32 v151, v151
	v_mul_f32_e32 v152, 0xbfb8aa3b, v152
	v_exp_f32_e32 v152, v152
	v_add_f32_e32 v153, v58, v142
	v_add_f32_e32 v151, 1.0, v151
	v_rcp_f32_e32 v151, v151
	v_add_f32_e32 v152, 1.0, v152
	v_rcp_f32_e32 v175, v152
	v_mul_f32_e32 v153, 0xbfb8aa3b, v153
	v_mul_f32_e32 v151, v152, v151
	v_add_f32_e32 v152, v66, v146
	v_mul_f32_e32 v152, 0xbfb8aa3b, v152
	v_exp_f32_e32 v152, v152
	v_exp_f32_e32 v153, v153
	v_exp_f32_e32 v154, v154
	v_add_f32_e32 v155, v52, v132
	v_add_f32_e32 v152, 1.0, v152
	v_rcp_f32_e32 v152, v152
	v_add_f32_e32 v153, 1.0, v153
	v_rcp_f32_e32 v178, v153
	v_add_f32_e32 v154, 1.0, v154
	v_mul_f32_e32 v152, v153, v152
	v_add_f32_e32 v153, v67, v147
	v_mul_f32_e32 v153, 0xbfb8aa3b, v153
	v_exp_f32_e32 v153, v153
	v_rcp_f32_e32 v179, v154
	v_mul_f32_e32 v155, 0xbfb8aa3b, v155
	v_exp_f32_e32 v155, v155
	v_add_f32_e32 v153, 1.0, v153
	v_rcp_f32_e32 v153, v153
	v_mul_f32_e32 v176, 0xbfb8aa3b, v176
	v_add_f32_e32 v155, 1.0, v155
	v_rcp_f32_e32 v180, v155
	v_mul_f32_e32 v153, v154, v153
	v_add_f32_e32 v154, v60, v136
	v_mul_f32_e32 v154, 0xbfb8aa3b, v154
	v_exp_f32_e32 v154, v154
	v_exp_f32_e32 v176, v176
	v_add_f32_e32 v177, v54, v134
	v_mul_f32_e32 v177, 0xbfb8aa3b, v177
	v_add_f32_e32 v154, 1.0, v154
	v_rcp_f32_e32 v154, v154
	v_add_f32_e32 v176, 1.0, v176
	v_rcp_f32_e32 v181, v176
	v_exp_f32_e32 v177, v177
	v_mul_f32_e32 v154, v155, v154
	v_add_f32_e32 v155, v61, v137
	v_mul_f32_e32 v155, 0xbfb8aa3b, v155
	v_exp_f32_e32 v155, v155
	v_add_f32_e32 v177, 1.0, v177
	v_rcp_f32_e32 v182, v177
	v_add_f32_e32 v183, v55, v135
	v_add_f32_e32 v155, 1.0, v155
	v_rcp_f32_e32 v155, v155
	v_mul_f32_e32 v183, 0xbfb8aa3b, v183
	v_exp_f32_e32 v183, v183
	v_cvt_pk_bf16_f32 v150, v150, v151
	v_mul_f32_e32 v155, v176, v155
	v_add_f32_e32 v176, v62, v138
	v_mul_f32_e32 v176, 0xbfb8aa3b, v176
	v_exp_f32_e32 v176, v176
	v_add_f32_e32 v183, 1.0, v183
	v_cvt_pk_bf16_f32 v151, v152, v153
	v_cvt_pk_bf16_f32 v152, v154, v155
	v_add_f32_e32 v176, 1.0, v176
	v_rcp_f32_e32 v176, v176
	v_lshl_add_u64 v[154:155], v[148:149], 0, s[14:15]
	v_rcp_f32_e32 v184, v183
	v_mul_f32_e32 v176, v177, v176
	v_add_f32_e32 v177, v63, v139
	v_mul_f32_e32 v177, 0xbfb8aa3b, v177
	v_exp_f32_e32 v177, v177
	s_nop 0
	v_add_f32_e32 v177, 1.0, v177
	v_rcp_f32_e32 v177, v177
	s_nop 0
	v_mul_f32_e32 v177, v183, v177
	v_cvt_pk_bf16_f32 v153, v176, v177
	v_lshl_add_u64 v[176:177], s[44:45], 0, v[154:155]
	global_store_dwordx4 v[176:177], v[150:153], off
	v_lshl_add_u64 v[154:155], s[46:47], 0, v[154:155]
	v_add_f32_e32 v176, v37, v133
	v_cvt_pk_bf16_f32 v150, v160, v175
	v_cvt_pk_bf16_f32 v151, v178, v179
	v_cvt_pk_bf16_f32 v152, v180, v181
	v_cvt_pk_bf16_f32 v153, v182, v184
	global_store_dwordx4 v[154:155], v[150:153], off
	v_add_f32_e32 v154, v43, v143
	v_mul_f32_e32 v154, 0xbfb8aa3b, v154
	v_add_f32_e32 v150, v48, v144
	v_mul_f32_e32 v150, 0xbfb8aa3b, v150
	v_exp_f32_e32 v150, v150
	v_add_f32_e32 v151, v40, v140
	v_mul_f32_e32 v151, 0xbfb8aa3b, v151
	v_exp_f32_e32 v151, v151
	v_add_f32_e32 v150, 1.0, v150
	v_rcp_f32_e32 v150, v150
	v_add_f32_e32 v152, v41, v141
	v_add_f32_e32 v151, 1.0, v151
	v_rcp_f32_e32 v160, v151
	v_mul_f32_e32 v150, v151, v150
	v_add_f32_e32 v151, v49, v145
	v_mul_f32_e32 v151, 0xbfb8aa3b, v151
	v_exp_f32_e32 v151, v151
	v_mul_f32_e32 v152, 0xbfb8aa3b, v152
	v_exp_f32_e32 v152, v152
	v_add_f32_e32 v153, v42, v142
	v_add_f32_e32 v151, 1.0, v151
	v_rcp_f32_e32 v151, v151
	v_add_f32_e32 v152, 1.0, v152
	v_rcp_f32_e32 v175, v152
	v_mul_f32_e32 v153, 0xbfb8aa3b, v153
	v_mul_f32_e32 v151, v152, v151
	v_add_f32_e32 v152, v50, v146
	v_mul_f32_e32 v152, 0xbfb8aa3b, v152
	v_exp_f32_e32 v152, v152
	v_exp_f32_e32 v153, v153
	v_exp_f32_e32 v154, v154
	v_add_f32_e32 v155, v36, v132
	v_add_f32_e32 v152, 1.0, v152
	v_rcp_f32_e32 v152, v152
	v_add_f32_e32 v153, 1.0, v153
	v_rcp_f32_e32 v178, v153
	v_add_f32_e32 v154, 1.0, v154
	v_mul_f32_e32 v152, v153, v152
	v_add_f32_e32 v153, v51, v147
	v_mul_f32_e32 v153, 0xbfb8aa3b, v153
	v_exp_f32_e32 v153, v153
	v_rcp_f32_e32 v179, v154
	v_mul_f32_e32 v155, 0xbfb8aa3b, v155
	v_exp_f32_e32 v155, v155
	v_add_f32_e32 v153, 1.0, v153
	v_rcp_f32_e32 v153, v153
	v_mul_f32_e32 v176, 0xbfb8aa3b, v176
	v_add_f32_e32 v155, 1.0, v155
	v_rcp_f32_e32 v180, v155
	v_mul_f32_e32 v153, v154, v153
	v_add_f32_e32 v154, v44, v136
	v_mul_f32_e32 v154, 0xbfb8aa3b, v154
	v_exp_f32_e32 v154, v154
	v_exp_f32_e32 v176, v176
	v_add_f32_e32 v177, v38, v134
	v_mul_f32_e32 v177, 0xbfb8aa3b, v177
	v_add_f32_e32 v154, 1.0, v154
	v_rcp_f32_e32 v154, v154
	v_add_f32_e32 v176, 1.0, v176
	v_rcp_f32_e32 v181, v176
	v_exp_f32_e32 v177, v177
	v_mul_f32_e32 v154, v155, v154
	v_add_f32_e32 v155, v45, v137
	v_mul_f32_e32 v155, 0xbfb8aa3b, v155
	v_exp_f32_e32 v155, v155
	v_add_f32_e32 v177, 1.0, v177
	v_rcp_f32_e32 v182, v177
	v_add_f32_e32 v183, v39, v135
	v_add_f32_e32 v155, 1.0, v155
	v_rcp_f32_e32 v155, v155
	v_mul_f32_e32 v183, 0xbfb8aa3b, v183
	v_exp_f32_e32 v183, v183
	v_cvt_pk_bf16_f32 v150, v150, v151
	v_mul_f32_e32 v155, v176, v155
	v_add_f32_e32 v176, v46, v138
	v_mul_f32_e32 v176, 0xbfb8aa3b, v176
	v_exp_f32_e32 v176, v176
	v_add_f32_e32 v183, 1.0, v183
	v_cvt_pk_bf16_f32 v151, v152, v153
	v_cvt_pk_bf16_f32 v152, v154, v155
	v_add_f32_e32 v176, 1.0, v176
	v_rcp_f32_e32 v176, v176
	v_lshl_add_u64 v[154:155], v[148:149], 0, s[4:5]
	v_rcp_f32_e32 v184, v183
	s_mov_b64 s[4:5], 0x58000
	v_mul_f32_e32 v176, v177, v176
	v_add_f32_e32 v177, v47, v139
	v_mul_f32_e32 v177, 0xbfb8aa3b, v177
	v_exp_f32_e32 v177, v177
	s_nop 0
	v_add_f32_e32 v177, 1.0, v177
	v_rcp_f32_e32 v177, v177
	s_nop 0
	v_mul_f32_e32 v177, v183, v177
	v_cvt_pk_bf16_f32 v153, v176, v177
	v_lshl_add_u64 v[176:177], s[44:45], 0, v[154:155]
	global_store_dwordx4 v[176:177], v[150:153], off
	v_lshl_add_u64 v[154:155], s[46:47], 0, v[154:155]
	v_add_f32_e32 v176, v21, v133
	v_cvt_pk_bf16_f32 v150, v160, v175
	v_cvt_pk_bf16_f32 v151, v178, v179
	v_cvt_pk_bf16_f32 v152, v180, v181
	v_cvt_pk_bf16_f32 v153, v182, v184
	global_store_dwordx4 v[154:155], v[150:153], off
	v_add_f32_e32 v154, v27, v143
	v_mul_f32_e32 v154, 0xbfb8aa3b, v154
	v_add_f32_e32 v150, v32, v144
	v_mul_f32_e32 v150, 0xbfb8aa3b, v150
	v_exp_f32_e32 v150, v150
	v_add_f32_e32 v151, v24, v140
	v_mul_f32_e32 v151, 0xbfb8aa3b, v151
	v_exp_f32_e32 v151, v151
	v_add_f32_e32 v150, 1.0, v150
	v_rcp_f32_e32 v150, v150
	v_add_f32_e32 v152, v25, v141
	v_add_f32_e32 v151, 1.0, v151
	v_rcp_f32_e32 v160, v151
	v_mul_f32_e32 v150, v151, v150
	v_add_f32_e32 v151, v33, v145
	v_mul_f32_e32 v151, 0xbfb8aa3b, v151
	v_exp_f32_e32 v151, v151
	v_mul_f32_e32 v152, 0xbfb8aa3b, v152
	v_exp_f32_e32 v152, v152
	v_add_f32_e32 v153, v26, v142
	v_add_f32_e32 v151, 1.0, v151
	v_rcp_f32_e32 v151, v151
	v_add_f32_e32 v152, 1.0, v152
	v_rcp_f32_e32 v175, v152
	v_mul_f32_e32 v153, 0xbfb8aa3b, v153
	v_mul_f32_e32 v151, v152, v151
	v_add_f32_e32 v152, v34, v146
	v_mul_f32_e32 v152, 0xbfb8aa3b, v152
	v_exp_f32_e32 v152, v152
	v_exp_f32_e32 v153, v153
	v_exp_f32_e32 v154, v154
	v_add_f32_e32 v155, v20, v132
	v_add_f32_e32 v152, 1.0, v152
	v_rcp_f32_e32 v152, v152
	v_add_f32_e32 v153, 1.0, v153
	v_rcp_f32_e32 v178, v153
	v_add_f32_e32 v154, 1.0, v154
	v_mul_f32_e32 v152, v153, v152
	v_add_f32_e32 v153, v35, v147
	v_mul_f32_e32 v153, 0xbfb8aa3b, v153
	v_exp_f32_e32 v153, v153
	v_rcp_f32_e32 v179, v154
	v_mul_f32_e32 v155, 0xbfb8aa3b, v155
	v_exp_f32_e32 v155, v155
	v_add_f32_e32 v153, 1.0, v153
	v_rcp_f32_e32 v153, v153
	v_mul_f32_e32 v176, 0xbfb8aa3b, v176
	v_add_f32_e32 v155, 1.0, v155
	v_rcp_f32_e32 v180, v155
	v_mul_f32_e32 v153, v154, v153
	v_add_f32_e32 v154, v28, v136
	v_mul_f32_e32 v154, 0xbfb8aa3b, v154
	v_exp_f32_e32 v154, v154
	v_exp_f32_e32 v176, v176
	v_add_f32_e32 v177, v22, v134
	v_mul_f32_e32 v177, 0xbfb8aa3b, v177
	v_add_f32_e32 v154, 1.0, v154
	v_rcp_f32_e32 v154, v154
	v_add_f32_e32 v176, 1.0, v176
	v_rcp_f32_e32 v181, v176
	v_exp_f32_e32 v177, v177
	v_mul_f32_e32 v154, v155, v154
	v_add_f32_e32 v155, v29, v137
	v_mul_f32_e32 v155, 0xbfb8aa3b, v155
	v_exp_f32_e32 v155, v155
	v_add_f32_e32 v177, 1.0, v177
	v_rcp_f32_e32 v182, v177
	v_add_f32_e32 v144, v16, v144
	v_add_f32_e32 v155, 1.0, v155
	v_rcp_f32_e32 v155, v155
	v_add_f32_e32 v183, v23, v135
	v_mul_f32_e32 v144, 0xbfb8aa3b, v144
	v_mul_f32_e32 v183, 0xbfb8aa3b, v183
	v_mul_f32_e32 v155, v176, v155
	v_add_f32_e32 v176, v30, v138
	v_mul_f32_e32 v176, 0xbfb8aa3b, v176
	v_exp_f32_e32 v176, v176
	v_exp_f32_e32 v144, v144
	v_exp_f32_e32 v183, v183
	v_add_f32_e32 v140, v8, v140
	v_add_f32_e32 v176, 1.0, v176
	v_rcp_f32_e32 v176, v176
	v_mul_f32_e32 v140, 0xbfb8aa3b, v140
	v_add_f32_e32 v144, 1.0, v144
	v_exp_f32_e32 v140, v140
	v_mul_f32_e32 v176, v177, v176
	v_add_f32_e32 v177, v31, v139
	v_mul_f32_e32 v177, 0xbfb8aa3b, v177
	v_exp_f32_e32 v177, v177
	v_add_f32_e32 v183, 1.0, v183
	v_rcp_f32_e32 v144, v144
	v_cvt_pk_bf16_f32 v150, v150, v151
	v_add_f32_e32 v177, 1.0, v177
	v_rcp_f32_e32 v177, v177
	v_cvt_pk_bf16_f32 v151, v152, v153
	v_cvt_pk_bf16_f32 v152, v154, v155
	v_lshl_add_u64 v[154:155], v[148:149], 0, s[18:19]
	v_mul_f32_e32 v177, v183, v177
	v_cvt_pk_bf16_f32 v153, v176, v177
	v_lshl_add_u64 v[176:177], s[44:45], 0, v[154:155]
	global_store_dwordx4 v[176:177], v[150:153], off
	v_lshl_add_u64 v[154:155], s[46:47], 0, v[154:155]
	v_add_f32_e32 v140, 1.0, v140
	v_cvt_pk_bf16_f32 v150, v160, v175
	v_rcp_f32_e32 v184, v183
	v_cvt_pk_bf16_f32 v151, v178, v179
	v_cvt_pk_bf16_f32 v152, v180, v181
	v_cvt_pk_bf16_f32 v153, v182, v184
	global_store_dwordx4 v[154:155], v[150:153], off
	v_add_f32_e32 v141, v9, v141
	v_mul_f32_e32 v141, 0xbfb8aa3b, v141
	v_rcp_f32_e32 v150, v140
	v_mul_f32_e32 v140, v140, v144
	v_add_f32_e32 v144, v17, v145
	v_mul_f32_e32 v144, 0xbfb8aa3b, v144
	v_exp_f32_e32 v144, v144
	v_exp_f32_e32 v141, v141
	v_add_f32_e32 v142, v10, v142
	v_mul_f32_e32 v142, 0xbfb8aa3b, v142
	v_add_f32_e32 v144, 1.0, v144
	v_rcp_f32_e32 v144, v144
	v_add_f32_e32 v141, 1.0, v141
	v_rcp_f32_e32 v145, v141
	v_exp_f32_e32 v142, v142
	v_mul_f32_e32 v141, v141, v144
	v_add_f32_e32 v144, v18, v146
	v_mul_f32_e32 v144, 0xbfb8aa3b, v144
	v_exp_f32_e32 v144, v144
	v_add_f32_e32 v142, 1.0, v142
	v_rcp_f32_e32 v146, v142
	v_add_f32_e32 v136, v12, v136
	v_add_f32_e32 v144, 1.0, v144
	v_rcp_f32_e32 v144, v144
	v_mul_f32_e32 v136, 0xbfb8aa3b, v136
	v_exp_f32_e32 v136, v136
	v_add_f32_e32 v143, v11, v143
	v_mul_f32_e32 v142, v142, v144
	v_add_f32_e32 v144, v19, v147
	v_mul_f32_e32 v144, 0xbfb8aa3b, v144
	v_exp_f32_e32 v144, v144
	v_add_f32_e32 v132, v4, v132
	v_mul_f32_e32 v143, 0xbfb8aa3b, v143
	v_mul_f32_e32 v132, 0xbfb8aa3b, v132
	v_add_f32_e32 v144, 1.0, v144
	v_exp_f32_e32 v143, v143
	v_add_f32_e32 v136, 1.0, v136
	v_exp_f32_e32 v132, v132
	v_rcp_f32_e32 v144, v144
	v_rcp_f32_e32 v136, v136
	v_add_f32_e32 v143, 1.0, v143
	v_add_f32_e32 v132, 1.0, v132
	v_rcp_f32_e32 v147, v143
	v_mul_f32_e32 v143, v143, v144
	v_rcp_f32_e32 v144, v132
	v_mul_f32_e32 v136, v132, v136
	v_add_f32_e32 v132, v13, v137
	v_mul_f32_e32 v132, 0xbfb8aa3b, v132
	v_exp_f32_e32 v132, v132
	v_add_f32_e32 v133, v5, v133
	v_mul_f32_e32 v133, 0xbfb8aa3b, v133
	v_exp_f32_e32 v133, v133
	v_add_f32_e32 v132, 1.0, v132
	v_rcp_f32_e32 v132, v132
	v_add_f32_e32 v133, 1.0, v133
	v_rcp_f32_e32 v151, v133
	v_mul_f32_e32 v137, v133, v132
	v_add_f32_e32 v132, v14, v138
	v_mul_f32_e32 v132, 0xbfb8aa3b, v132
	v_exp_f32_e32 v132, v132
	v_add_f32_e32 v133, v6, v134
	v_mul_f32_e32 v133, 0xbfb8aa3b, v133
	v_exp_f32_e32 v133, v133
	v_add_f32_e32 v132, 1.0, v132
	v_rcp_f32_e32 v132, v132
	v_add_f32_e32 v133, 1.0, v133
	v_rcp_f32_e32 v152, v133
	v_mul_f32_e32 v138, v133, v132
	v_add_f32_e32 v132, v15, v139
	v_mul_f32_e32 v132, 0xbfb8aa3b, v132
	v_exp_f32_e32 v132, v132
	v_add_f32_e32 v133, v7, v135
	v_mul_f32_e32 v133, 0xbfb8aa3b, v133
	v_exp_f32_e32 v133, v133
	v_add_f32_e32 v132, 1.0, v132
	v_rcp_f32_e32 v132, v132
	v_add_f32_e32 v133, 1.0, v133
	v_rcp_f32_e32 v153, v133
	v_mul_f32_e32 v135, v133, v132
	v_cvt_pk_bf16_f32 v132, v140, v141
	v_cvt_pk_bf16_f32 v133, v142, v143
	v_cvt_pk_bf16_f32 v134, v136, v137
	v_lshl_add_u64 v[136:137], v[148:149], 0, s[4:5]
	v_cvt_pk_bf16_f32 v135, v138, v135
	v_lshl_add_u64 v[138:139], s[44:45], 0, v[136:137]
	v_lshl_add_u64 v[136:137], s[46:47], 0, v[136:137]
	global_store_dwordx4 v[138:139], v[132:135], off
	s_nop 1
	v_cvt_pk_bf16_f32 v132, v150, v145
	v_cvt_pk_bf16_f32 v133, v146, v147
	v_cvt_pk_bf16_f32 v134, v144, v151
	v_cvt_pk_bf16_f32 v135, v152, v153
	global_store_dwordx4 v[136:137], v[132:135], off
	s_cbranch_execz .LBB0_391

.LBB0_391:
	s_lshl_b32 s4, s96, 8
	s_or_b32 s67, s4, s85
	v_or_b32_e32 v176, s67, v191
	v_ashrrev_i32_e32 v177, 31, v176
	v_or_b32_e32 v136, s85, v191
	v_lshlrev_b32_e32 v136, 2, v136
	v_add_u32_e32 v136, 0x21000, v136
	v_add_u32_e32 v136, s99, v136
	ds_read_b128 v[140:143], v136 offset:16
	ds_read_b128 v[144:147], v136
	ds_read_b128 v[132:135], v136 offset:144
	ds_read_b128 v[136:139], v136 offset:128
	s_cmp_gt_i32 s96, 1
	s_mov_b64 s[4:5], -1
	s_cbranch_scc0 .LBB0_469
	s_cmp_gt_u32 s96, 3
	s_cbranch_scc0 .LBB0_450
	s_cmp_gt_u32 s96, 5
	s_cbranch_scc0 .LBB0_431
	s_cmp_lt_u32 s96, 10
	s_cbranch_scc1 .LBB0_412
	s_waitcnt lgkmcnt(0)
	v_pk_add_f32 v[150:151], v[128:129], v[144:145]
	v_pk_add_f32 v[154:155], v[124:125], v[140:141]
	v_mul_f32_e32 v160, 0x3d372713, v150
	v_mul_f32_e32 v160, v150, v160
	v_fma_f32 v160, v150, v160, v150
	v_mul_f32_e32 v160, 0x3fcc422a, v160
	v_mul_f32_e32 v160, 0xbfb8aa3b, v160
	v_exp_f32_e32 v160, v160
	v_mov_b64_e32 v[148:149], s[30:31]
	v_mad_i64_i32 v[148:149], s[4:5], v174, s13, v[148:149]
	v_add_f32_e32 v160, 1.0, v160
	v_rcp_f32_e32 v160, v160
	v_lshl_add_u64 v[178:179], v[176:177], 1, v[148:149]
	v_pk_add_f32 v[148:149], v[130:131], v[146:147]
	v_pk_add_f32 v[152:153], v[126:127], v[142:143]
	v_mul_f32_e32 v150, v150, v160
	v_mul_f32_e32 v160, 0x3d372713, v154
	v_mul_f32_e32 v160, v154, v160
	v_fma_f32 v160, v154, v160, v154
	v_mul_f32_e32 v160, 0x3fcc422a, v160
	v_mul_f32_e32 v160, 0xbfb8aa3b, v160
	v_exp_f32_e32 v160, v160
	s_movk_i32 s34, 0xf000
	s_movk_i32 s38, 0x9040
	s_mov_b32 s35, -1
	v_add_f32_e32 v160, 1.0, v160
	v_rcp_f32_e32 v160, v160
	s_mov_b32 s39, -1
	v_lshl_add_u64 v[182:183], v[178:179], 0, s[38:39]
	v_mul_f32_e32 v154, v154, v160
	v_mul_f32_e32 v160, 0x3d372713, v151
	v_mul_f32_e32 v160, v151, v160
	v_fma_f32 v160, v151, v160, v151
	v_mul_f32_e32 v160, 0x3fcc422a, v160
	v_mul_f32_e32 v160, 0xbfb8aa3b, v160
	v_exp_f32_e32 v160, v160
	s_nop 0
	v_add_f32_e32 v160, 1.0, v160
	v_rcp_f32_e32 v160, v160
	s_nop 0
	v_mul_f32_e32 v151, v151, v160
	v_mul_f32_e32 v160, 0x3d372713, v155
	v_mul_f32_e32 v160, v155, v160
	v_fma_f32 v160, v155, v160, v155
	v_mul_f32_e32 v160, 0x3fcc422a, v160
	v_mul_f32_e32 v160, 0xbfb8aa3b, v160
	v_exp_f32_e32 v160, v160
	s_nop 0
	v_add_f32_e32 v160, 1.0, v160
	v_rcp_f32_e32 v160, v160
	s_nop 0
	v_mul_f32_e32 v155, v155, v160
	v_mul_f32_e32 v160, 0x3d372713, v148
	v_mul_f32_e32 v160, v148, v160
	v_fma_f32 v160, v148, v160, v148
	v_mul_f32_e32 v160, 0x3fcc422a, v160
	v_mul_f32_e32 v160, 0xbfb8aa3b, v160
	v_exp_f32_e32 v160, v160
	s_nop 0
	v_add_f32_e32 v160, 1.0, v160
	v_rcp_f32_e32 v160, v160
	s_nop 0
	v_mul_f32_e32 v148, v148, v160
	v_mul_f32_e32 v160, 0x3d372713, v152
	v_mul_f32_e32 v160, v152, v160
	v_fma_f32 v160, v152, v160, v152
	v_mul_f32_e32 v160, 0x3fcc422a, v160
	v_mul_f32_e32 v160, 0xbfb8aa3b, v160
	v_exp_f32_e32 v160, v160
	s_nop 0
	v_add_f32_e32 v160, 1.0, v160
	v_rcp_f32_e32 v160, v160
	s_nop 0
	v_mul_f32_e32 v152, v152, v160
	v_mul_f32_e32 v160, 0x3d372713, v149
	v_mul_f32_e32 v160, v149, v160
	v_fma_f32 v160, v149, v160, v149
	v_mul_f32_e32 v160, 0x3fcc422a, v160
	v_mul_f32_e32 v160, 0xbfb8aa3b, v160
	v_exp_f32_e32 v160, v160
	s_nop 0
	v_add_f32_e32 v160, 1.0, v160
	v_rcp_f32_e32 v160, v160
	s_nop 0
	v_mul_f32_e32 v149, v149, v160
	v_mul_f32_e32 v160, 0x3d372713, v153
	v_mul_f32_e32 v160, v153, v160
	v_fma_f32 v160, v153, v160, v153
	v_mul_f32_e32 v160, 0x3fcc422a, v160
	v_mul_f32_e32 v160, 0xbfb8aa3b, v160
	v_exp_f32_e32 v160, v160
	s_nop 0
	v_add_f32_e32 v160, 1.0, v160
	v_rcp_f32_e32 v160, v160
	s_nop 0
	v_mul_f32_e32 v153, v153, v160
	v_cvt_pk_bf16_f32 v160, v150, v151
	v_pk_add_f32 v[150:151], v[120:121], v[136:137]
	v_cvt_pk_bf16_f32 v175, v148, v149
	v_cvt_pk_bf16_f32 v184, v154, v155
	v_pk_add_f32 v[154:155], v[116:117], v[132:133]
	v_mul_f32_e32 v180, 0x3d372713, v150
	v_mul_f32_e32 v180, v150, v180
	v_fma_f32 v180, v150, v180, v150
	v_mul_f32_e32 v180, 0x3fcc422a, v180
	v_mul_f32_e32 v180, 0xbfb8aa3b, v180
	v_exp_f32_e32 v180, v180
	v_pk_add_f32 v[148:149], v[122:123], v[138:139]
	v_cvt_pk_bf16_f32 v185, v152, v153
	v_pk_add_f32 v[152:153], v[118:119], v[134:135]
	v_add_f32_e32 v180, 1.0, v180
	v_rcp_f32_e32 v180, v180
	s_nop 0
	v_mul_f32_e32 v150, v150, v180
	v_mul_f32_e32 v180, 0x3d372713, v154
	v_mul_f32_e32 v180, v154, v180
	v_fma_f32 v180, v154, v180, v154
	v_mul_f32_e32 v180, 0x3fcc422a, v180
	v_mul_f32_e32 v180, 0xbfb8aa3b, v180
	v_exp_f32_e32 v180, v180
	s_nop 0
	v_add_f32_e32 v180, 1.0, v180
	v_rcp_f32_e32 v180, v180
	s_nop 0
	v_mul_f32_e32 v154, v154, v180
	v_mul_f32_e32 v180, 0x3d372713, v151
	v_mul_f32_e32 v180, v151, v180
	v_fma_f32 v180, v151, v180, v151
	v_mul_f32_e32 v180, 0x3fcc422a, v180
	v_mul_f32_e32 v180, 0xbfb8aa3b, v180
	v_exp_f32_e32 v180, v180
	s_nop 0
	v_add_f32_e32 v180, 1.0, v180
	v_rcp_f32_e32 v180, v180
	s_nop 0
	v_mul_f32_e32 v151, v151, v180
	v_mul_f32_e32 v180, 0x3d372713, v155
	v_mul_f32_e32 v180, v155, v180
	v_fma_f32 v180, v155, v180, v155
	v_mul_f32_e32 v180, 0x3fcc422a, v180
	v_mul_f32_e32 v180, 0xbfb8aa3b, v180
	v_exp_f32_e32 v180, v180
	v_cvt_pk_bf16_f32 v150, v150, v151
	s_nop 0
	v_add_f32_e32 v180, 1.0, v180
	v_rcp_f32_e32 v180, v180
	s_nop 0
	v_mul_f32_e32 v155, v155, v180
	v_mul_f32_e32 v180, 0x3d372713, v148
	v_mul_f32_e32 v180, v148, v180
	v_fma_f32 v180, v148, v180, v148
	v_mul_f32_e32 v180, 0x3fcc422a, v180
	v_mul_f32_e32 v180, 0xbfb8aa3b, v180
	v_exp_f32_e32 v180, v180
	s_nop 0
	v_add_f32_e32 v180, 1.0, v180
	v_rcp_f32_e32 v180, v180
	s_nop 0
	v_mul_f32_e32 v148, v148, v180
	v_mul_f32_e32 v180, 0x3d372713, v152
	v_mul_f32_e32 v180, v152, v180
	v_fma_f32 v180, v152, v180, v152
	v_mul_f32_e32 v180, 0x3fcc422a, v180
	v_mul_f32_e32 v180, 0xbfb8aa3b, v180
	v_exp_f32_e32 v180, v180
	s_nop 0
	v_add_f32_e32 v180, 1.0, v180
	v_rcp_f32_e32 v180, v180
	s_nop 0
	v_mul_f32_e32 v152, v152, v180
	v_mul_f32_e32 v180, 0x3d372713, v149
	v_mul_f32_e32 v180, v149, v180
	v_fma_f32 v180, v149, v180, v149
	v_mul_f32_e32 v180, 0x3fcc422a, v180
	v_mul_f32_e32 v180, 0xbfb8aa3b, v180
	v_exp_f32_e32 v180, v180
	s_nop 0
	v_add_f32_e32 v180, 1.0, v180
	v_rcp_f32_e32 v180, v180
	s_nop 0
	v_mul_f32_e32 v149, v149, v180
	v_mul_f32_e32 v180, 0x3d372713, v153
	v_mul_f32_e32 v180, v153, v180
	v_fma_f32 v180, v153, v180, v153
	v_mul_f32_e32 v180, 0x3fcc422a, v180
	v_mul_f32_e32 v180, 0xbfb8aa3b, v180
	v_exp_f32_e32 v180, v180
	v_cvt_pk_bf16_f32 v151, v148, v149
	v_mov_b32_e32 v148, 0
	v_mov_b32_e32 v149, 0
	v_add_f32_e32 v180, 1.0, v180
	v_rcp_f32_e32 v180, v180
	v_cvt_pk_bf16_f32 v154, v154, v155
	v_mov_b32_dpp v148, v150 row_ror:8 row_mask:0xf bank_mask:0xf
	v_mov_b32_dpp v149, v151 row_ror:8 row_mask:0xf bank_mask:0xf
	v_mul_f32_e32 v153, v153, v180
	v_cvt_pk_bf16_f32 v152, v152, v153
	v_mov_b32_e32 v150, 0
	v_mov_b32_e32 v151, 0
	v_lshl_add_u64 v[180:181], v[178:179], 0, s[34:35]
	v_mov_b32_dpp v150, v154 row_ror:8 row_mask:0xf bank_mask:0xf
	v_mov_b32_dpp v151, v152 row_ror:8 row_mask:0xf bank_mask:0xf
	v_mov_b32_e32 v152, v160
	v_mov_b32_e32 v153, v175
	v_mov_b32_e32 v154, v184
	v_mov_b32_e32 v155, v185
	s_and_saveexec_b64 s[4:5], s[6:7]
	s_mov_b64 s[82:83], 0x5040
	s_cbranch_execz .LBB0_397
	v_lshl_add_u64 v[178:179], v[178:179], 0, s[82:83]
	v_mov_b64_e32 v[182:183], v[180:181]
	v_mov_b32_e32 v152, v148
	v_mov_b32_e32 v153, v149
	v_mov_b32_e32 v154, v150
	v_mov_b32_e32 v155, v151
	v_mov_b32_e32 v148, v160
	v_mov_b32_e32 v149, v175
	v_mov_b32_e32 v150, v184
	v_mov_b32_e32 v151, v185
	v_mov_b64_e32 v[180:181], v[178:179]

.LBB0_488:
	v_readlane_b32 s4, v254, 22
	v_readlane_b32 s5, v254, 23
	s_andn2_b64 vcc, exec, s[4:5]
	s_cbranch_vccnz .LBB0_379
	s_branch .LBB0_379
